# attention: packed v_pk_mul_f32 of the output accumulators (feeding the PV MFMAs) as scalar v_mul pairs
# speedup vs baseline: 1.0005x; 1.0005x over previous
; #define LAS __attribute__((address_space(3)))
; DI unsigned cvtpk(float lo, float hi) { const f32x2 v = (f32x2){lo, hi}; const bf16x2_t b = __builtin_convertvector(v, bf16x2_t); return __builtin_bit_cast(unsigned, b); }
; #define MFMA16(a, b, c) __builtin_amdgcn_mfma_f32_16x16x32_bf16((a), (b), (c), 0, 0, 0)
; DI void attn_phase(const PZ& p, LAS unsigned char* lds, int tid, int wave, int lane) {
;     ...
;             for (int mt = 0; mt < 2; ++mt) {
;                 float mx = sacc[0][mt][0];
; #pragma unroll
;                 for (int nt = 0; nt < 4; ++nt)
; #pragma unroll
;                     for (int j = 0; j < 4; ++j) mx = fmaxf(mx, sacc[nt][mt][j]);
;                 mx = fmaxf(mx, __shfl_xor(mx, 16)); mx = fmaxf(mx, __shfl_xor(mx, 32));
;                 const float mnew = fmaxf(mrow[mt], mx);
;                 const float alpha = __builtin_amdgcn_exp2f(mrow[mt] - mnew);
;                 mrow[mt] = mnew;
;                 float ls = lrow[mt] * alpha;
; #pragma unroll
;                 for (int nt = 0; nt < 4; ++nt)
; #pragma unroll
;                     for (int j = 0; j < 4; ++j) { const float pe = __builtin_amdgcn_exp2f(sacc[nt][mt][j] - mnew); sacc[nt][mt][j] = pe; ls += pe; }
;                 lrow[mt] = ls;
; #pragma unroll
;                 for (int md = 0; md < 4; ++md) oacc[md][mt] *= alpha;
;             }
; #pragma unroll
;             for (int kp = 0; kp < 2; ++kp) {
;                 bf16x8 pB[2];
; #pragma unroll
;                 for (int mt = 0; mt < 2; ++mt) {
;                     const f32x4 x0 = sacc[2 * kp][mt], x1 = sacc[2 * kp + 1][mt];
;                     pB[mt] = mk8((u32x2){cvtpk(x0.x, x0.y), cvtpk(x0.z, x0.w)}, (u32x2){cvtpk(x1.x, x1.y), cvtpk(x1.z, x1.w)});
;                 }
; #pragma unroll
;                 for (int md = 0; md < 4; ++md) {
;                     const bf16x8 vA = mk8(*(const LAS u32x2*)(Vs + (md * 16 + l15) * 72 + (2 * kp) * 16 + g * 4), *(const LAS u32x2*)(Vs + (md * 16 + l15) * 72 + (2 * kp + 1) * 16 + g * 4));
; #pragma unroll
;                     for (int mt = 0; mt < 2; ++mt) oacc[md][mt] = MFMA16(vA, pB[mt], oacc[md][mt]);
;                 }
.LBB0_136:
	v_max_f32_e32 v112, v89, v89
	v_max_f32_e32 v113, v88, v88
	v_max_f32_e32 v112, v113, v112
	v_max3_f32 v112, v112, v90, v91
	v_max3_f32 v112, v112, v80, v81
	v_max3_f32 v112, v112, v82, v83
	v_max3_f32 v112, v112, v76, v77
	v_max3_f32 v112, v112, v78, v79
	v_max3_f32 v112, v112, v84, v85
	v_max3_f32 v112, v112, v86, v87
	v_mov_b32_e32 v113, v112
	s_lshl_b32 s8, s8, 1
	s_add_i32 s8, s8, 0
	s_andn2_b64 vcc, exec, s[24:25]
	s_waitcnt lgkmcnt(0)
	v_permlane16_swap_b32_e32 v112, v113
	v_max_f32_e32 v112, v112, v113
	v_mov_b32_e32 v113, v112
	s_nop 1
	v_permlane32_swap_b32_e32 v112, v113
	s_waitcnt lgkmcnt(0)
	v_max3_f32 v142, v110, v112, v113
	v_sub_f32_e32 v76, v76, v142
	v_exp_f32_e32 v120, v76
	v_sub_f32_e32 v76, v77, v142
	v_exp_f32_e32 v118, v76
	v_sub_f32_e32 v76, v78, v142
	v_sub_f32_e32 v110, v110, v142
	v_exp_f32_e32 v116, v76
	v_sub_f32_e32 v76, v79, v142
	v_exp_f32_e32 v110, v110
	v_sub_f32_e32 v89, v89, v142
	v_sub_f32_e32 v80, v80, v142
	v_exp_f32_e32 v114, v76
	v_sub_f32_e32 v76, v84, v142
	v_exp_f32_e32 v112, v89
	v_sub_f32_e32 v89, v90, v142
	v_exp_f32_e32 v128, v80
	v_sub_f32_e32 v80, v81, v142
	v_exp_f32_e32 v90, v76
	v_sub_f32_e32 v76, v85, v142
	v_exp_f32_e32 v126, v80
	v_sub_f32_e32 v80, v82, v142
	v_exp_f32_e32 v84, v76
	v_sub_f32_e32 v76, v86, v142
	v_exp_f32_e32 v124, v80
	v_sub_f32_e32 v80, v83, v142
	v_exp_f32_e32 v82, v76
	v_sub_f32_e32 v76, v87, v142
	v_exp_f32_e32 v122, v80
	v_exp_f32_e32 v80, v76
	v_mul_f32_e32 v76, v52, v110
	v_mul_f32_e32 v77, v53, v110
	v_mul_f32_e32 v52, v44, v110
	v_mul_f32_e32 v53, v45, v110
	v_mul_f32_e32 v44, v48, v110
	v_mul_f32_e32 v45, v49, v110
	v_max_f32_e32 v48, v69, v69
	v_max_f32_e32 v49, v68, v68
	v_max_f32_e32 v48, v49, v48
	v_max3_f32 v48, v48, v70, v71
	v_max3_f32 v48, v48, v60, v61
	v_max3_f32 v48, v48, v62, v63
	v_max3_f32 v48, v48, v64, v65
	v_max3_f32 v48, v48, v66, v67
	v_max3_f32 v48, v48, v72, v73
	v_max3_f32 v48, v48, v74, v75
	v_mov_b32_e32 v49, v48
	v_exp_f32_e32 v132, v89
	v_sub_f32_e32 v89, v91, v142
	v_exp_f32_e32 v130, v89
	v_mul_f32_e32 v78, v54, v110
	v_mul_f32_e32 v79, v55, v110
	s_waitcnt lgkmcnt(0)
	v_permlane16_swap_b32_e32 v48, v49
	v_max_f32_e32 v48, v48, v49
	v_mov_b32_e32 v49, v48
	v_mul_f32_e32 v58, v58, v110
	v_mul_f32_e32 v59, v59, v110
	v_mul_f32_e32 v56, v56, v110
	v_mul_f32_e32 v57, v57, v110
	v_mul_f32_e32 v54, v46, v110
	v_mul_f32_e32 v55, v47, v110
	v_mul_f32_e32 v46, v50, v110
	v_mul_f32_e32 v47, v51, v110
	s_waitcnt lgkmcnt(0)
	v_permlane32_swap_b32_e32 v48, v49
	v_max3_f32 v87, v111, v48, v49
	v_sub_f32_e32 v48, v111, v87
	v_exp_f32_e32 v86, v48
	v_sub_f32_e32 v48, v68, v87
	v_exp_f32_e32 v89, v48
	v_sub_f32_e32 v48, v69, v87
	v_exp_f32_e32 v113, v48
	v_sub_f32_e32 v48, v70, v87
	v_exp_f32_e32 v133, v48
	v_sub_f32_e32 v48, v71, v87
	v_exp_f32_e32 v131, v48
	v_sub_f32_e32 v48, v60, v87
	v_exp_f32_e32 v129, v48
	v_sub_f32_e32 v48, v61, v87
	v_exp_f32_e32 v127, v48
	v_sub_f32_e32 v48, v62, v87
	v_exp_f32_e32 v125, v48
	v_sub_f32_e32 v48, v63, v87
	v_exp_f32_e32 v123, v48
	v_sub_f32_e32 v48, v64, v87
	v_exp_f32_e32 v121, v48
	v_sub_f32_e32 v48, v65, v87
	v_exp_f32_e32 v119, v48
	v_sub_f32_e32 v48, v66, v87
	v_exp_f32_e32 v117, v48
	v_sub_f32_e32 v48, v67, v87
	v_lshlrev_b32_e32 v111, 1, v135
	v_exp_f32_e32 v115, v48
	v_sub_f32_e32 v48, v72, v87
	v_add3_u32 v72, s8, v138, v111
	v_add_u32_e32 v143, 0x4800, v72
	ds_read2_b64 v[68:71], v143 offset1:4
	v_sub_f32_e32 v88, v88, v142
	v_exp_f32_e32 v88, v88
	v_exp_f32_e32 v91, v48
	v_sub_f32_e32 v48, v73, v87
	v_exp_f32_e32 v85, v48
	v_sub_f32_e32 v48, v74, v87
	v_exp_f32_e32 v83, v48
	v_sub_f32_e32 v48, v75, v87
	v_pk_mul_f32 v[42:43], v[42:43], v[86:87] op_sel_hi:[1,0]
	v_pk_mul_f32 v[40:41], v[40:41], v[86:87] op_sel_hi:[1,0]
	v_pk_mul_f32 v[62:63], v[38:39], v[86:87] op_sel_hi:[1,0]
	v_pk_mul_f32 v[60:61], v[36:37], v[86:87] op_sel_hi:[1,0]
	v_pk_mul_f32 v[66:67], v[34:35], v[86:87] op_sel_hi:[1,0]
	v_pk_mul_f32 v[64:65], v[32:33], v[86:87] op_sel_hi:[1,0]
	v_cvt_pk_bf16_f32 v32, v88, v112
	v_cvt_pk_bf16_f32 v33, v132, v130
	v_cvt_pk_bf16_f32 v34, v128, v126
	v_cvt_pk_bf16_f32 v35, v124, v122
	v_cvt_pk_bf16_f32 v36, v89, v113
	v_cvt_pk_bf16_f32 v37, v133, v131
	v_cvt_pk_bf16_f32 v38, v129, v127
	v_cvt_pk_bf16_f32 v39, v125, v123
	v_add_u32_e32 v148, 0x5000, v72
	v_exp_f32_e32 v81, v48
	s_waitcnt lgkmcnt(0)
	v_mfma_f32_16x16x32_bf16 v[48:51], v[68:71], v[32:35], v[76:79]
	v_add_u32_e32 v149, 0x5800, v72
	v_pk_mul_f32 v[30:31], v[30:31], v[86:87] op_sel_hi:[1,0]
	v_pk_mul_f32 v[28:29], v[28:29], v[86:87] op_sel_hi:[1,0]
	v_mfma_f32_16x16x32_bf16 v[40:43], v[68:71], v[36:39], v[40:43]
	ds_read2_b64 v[68:71], v148 offset0:32 offset1:36
	v_cvt_pk_bf16_f32 v76, v120, v118
	v_cvt_pk_bf16_f32 v77, v116, v114
	s_waitcnt lgkmcnt(0)
	v_mfma_f32_16x16x32_bf16 v[56:59], v[68:71], v[32:35], v[56:59]
	v_cvt_pk_bf16_f32 v78, v90, v84
	v_cvt_pk_bf16_f32 v79, v82, v80
	v_cvt_pk_bf16_f32 v144, v121, v119
	v_mfma_f32_16x16x32_bf16 v[60:63], v[68:71], v[36:39], v[60:63]
	ds_read2_b64 v[68:71], v149 offset0:64 offset1:68
	v_cvt_pk_bf16_f32 v145, v117, v115
	v_cvt_pk_bf16_f32 v146, v91, v85
	s_waitcnt lgkmcnt(0)
	v_mfma_f32_16x16x32_bf16 v[72:75], v[68:71], v[32:35], v[52:55]
	s_nop 2
	v_add3_u32 v52, s8, v139, v111
	v_add_u32_e32 v111, 0x4800, v52
	ds_read2_b64 v[52:55], v111 offset1:4
	v_mfma_f32_16x16x32_bf16 v[64:67], v[68:71], v[36:39], v[64:67]
	v_cvt_pk_bf16_f32 v147, v83, v81
	s_waitcnt lgkmcnt(0)
	v_mfma_f32_16x16x32_bf16 v[68:71], v[52:55], v[32:35], v[44:47]
	ds_read2_b64 v[32:35], v143 offset0:8 offset1:12
	v_mfma_f32_16x16x32_bf16 v[28:31], v[52:55], v[36:39], v[28:31]
	s_waitcnt lgkmcnt(0)
	v_mfma_f32_16x16x32_bf16 v[52:55], v[32:35], v[76:79], v[48:51]
	v_mfma_f32_16x16x32_bf16 v[40:43], v[32:35], v[144:147], v[40:43]
	ds_read2_b64 v[32:35], v148 offset0:40 offset1:44
	s_waitcnt lgkmcnt(0)
	v_mfma_f32_16x16x32_bf16 v[56:59], v[32:35], v[76:79], v[56:59]
	v_mfma_f32_16x16x32_bf16 v[36:39], v[32:35], v[144:147], v[60:63]
	ds_read2_b64 v[32:35], v149 offset0:72 offset1:76
	s_nop 1
	ds_read2_b64 v[60:63], v111 offset0:8 offset1:12
	s_waitcnt lgkmcnt(1)
	v_mfma_f32_16x16x32_bf16 v[44:47], v[32:35], v[76:79], v[72:75]
	v_mfma_f32_16x16x32_bf16 v[32:35], v[32:35], v[144:147], v[64:67]
	s_waitcnt lgkmcnt(0)
	v_mfma_f32_16x16x32_bf16 v[48:51], v[60:63], v[76:79], v[68:71]
	v_mfma_f32_16x16x32_bf16 v[28:31], v[60:63], v[144:147], v[28:31]
	s_cbranch_vccnz .LBB0_138
	s_bitcmp1_b32 s7, 0
	s_cselect_b32 s8, 0x2400, 0
	v_add_u32_e32 v60, s8, v95
	s_waitcnt vmcnt(1)
	ds_write_b128 v60, v[20:23]
	s_waitcnt vmcnt(0)
	ds_write_b128 v60, v[24:27] offset:18432
